# attention phases: one static s_setprio 1 for waves 4-7 at phase entry, reset at exit (two same-program waves per SIMD)
# speedup vs baseline: 1.0038x; 1.0038x over previous
; DI int ltid() { int t = threadIdx.x; asm volatile("" : "+v"(t)); return t; }
; template <int TYPE>
; DI void attn_item(const Params& p, int layer, int head, int qt, int dil, int res, int chunk, char* smem) {
;   const int tid = ltid(), lane = tid & 63, wid = tid >> 6, ql = lane & 31, h = lane >> 5;
;   const u16* proj = (const u16*)(p.ws + OFF_BIG);
;   constexpr int QC = TYPE == 0 ? 0 : TYPE == 1 ? 1152 : 1920;
;   constexpr int KC = TYPE == 0 ? 384 : TYPE == 1 ? 1408 : 2304;
;   constexpr int VC = TYPE == 0 ? 768 : TYPE == 1 ? 1664 : 2688;
;   const int qcol = QC + head * 64, kcol = KC + head * 64, vcol = VC + head * 64;
;   const int Q0 = qt * 256;
;   const int wq0 = Q0 + 32 * wid;
;   const int Uq = wq0 + ql;
;   const size_t tq = (size_t)Uq * dil + res;
;   bf16x8 qf[4];
; #pragma unroll
;   for (int ks = 0; ks < 4; ++ks) qf[ks] = *(const bf16x8*)(proj + tq * DIN + qcol + ks * 16 + h * 8);
;   char* sK = smem;
;   char* sV = smem + 8192;
;   volatile int* sflag = (volatile int*)(smem + FLG + 32);
;   volatile float* dred = (volatile float*)(smem + FLG + 96);
;   float slope = 0.f;
;   if (TYPE == 0) slope = exp2f(-8.f * (float)(head + 1) / 6.f) * (float)dil * LOG2E;
;   if (TYPE == 1) slope = exp2f(-2.f * (float)(head + 1)) * LOG2E;
;   const int wlim = (TYPE == 0) ? 128 : 0x3fffffff;
;   int kt_hi = (Q0 >> 6) + 3;
; DI void attn_phase(const Params& p, int layer, char* smem) {
;   int* counter = (int*)(p.ws + OFF_MISC) + layer * 4;
;   volatile int* s_item = (volatile int*)(smem + FLG);
;   for (;;) {
;     __syncthreads();
;     if (threadIdx.x == 0) *s_item = atomicAdd(counter, 1);
;     __syncthreads();
;     const int item = *s_item;
;     if (item >= 64 * (NCH3 + NCH2 + 2)) break;
;     int head, qt, ch;
;     if (item < 64 * NCH3) { head = 3; qt = 63 - item / NCH3; ch = (item % NCH3) | (NCH3 << 8); }
;     else if (item < 64 * (NCH3 + NCH2)) { const int j = item - 64 * NCH3; head = 2; qt = 63 - j / NCH2; ch = (j % NCH2) | (NCH2 << 8); }
;     else if (item < 64 * (NCH3 + NCH2 + 1)) { head = 1; qt = 63 - (item - 64 * (NCH3 + NCH2)); ch = 1 << 8; }
;     else { head = 0; qt = 63 - (item - 64 * (NCH3 + NCH2 + 1)); ch = 1 << 8; }
;     attn_item<1>(p, layer, head, qt, 1, 0, ch, smem);
;   }
;   for (;;) {
;     __syncthreads();
;     if (threadIdx.x == 0) *s_item = atomicAdd(counter + 1, 1);
.LBB0_173:
	v_writelane_b32 v242, s91, 0
	s_or_b64 exec, exec, s[0:1]
	s_add_u32 s28, s24, 0xef00000
	s_addc_u32 s29, s25, 0
	s_add_u32 s34, s24, 0xef00230
	s_addc_u32 s35, s25, 0
	v_mbcnt_hi_u32_b32 v164, -1, v144
	s_mov_b64 s[6:7], src_shared_base
	s_add_u32 s16, s24, 0xb000000
	s_mov_b32 s52, 0x41c00000
	s_mov_b32 s54, 2.0
	s_mov_b32 s56, 0x41000000
	s_mov_b32 s58, 0x41200000
	s_mov_b32 s60, 0x41800000
	s_mov_b32 s62, 0x41900000
	s_mov_b32 s64, 0x41d00000
	v_and_b32_e32 v0, 64, v164
	s_addc_u32 s17, s25, 0
	s_mov_b64 s[36:37], 0
	v_mov_b32_e32 v1, 0
	v_mov_b32_e32 v122, 0x24000
	v_mov_b32_e32 v125, s7
	v_mov_b32_e32 v126, 0x24000
	v_mov_b32_e32 v127, s7
	s_movk_i32 s6, 0x180
	s_movk_i32 s33, 0x80
	s_movk_i32 s82, 0x7f
	s_movk_i32 s83, 0xff
	s_movk_i32 s84, 0x13f
	s_movk_i32 s85, 0x1800
	s_mov_b32 s86, 0x3fb8aa3b
	s_mov_b32 s87, 0xf800000
	v_mov_b32_e32 v167, 0x260
	v_mov_b32_e32 v168, 0x3c23d70a
	s_mov_b32 s53, 0x41c80000
	s_mov_b32 s55, 0x40400000
	s_mov_b32 s57, 0x41100000
	s_mov_b32 s59, 0x41300000
	s_mov_b32 s61, 0x41880000
	s_mov_b32 s63, 0x41980000
	s_mov_b32 s65, 0x41d80000
	s_mov_b32 s88, 0xc2ce8ed0
	s_mov_b32 s89, 0x42b17218
	v_mov_b32_e32 v128, 0x3e4ccccc
	s_movk_i32 s90, 0x880
	s_mov_b64 s[66:67], 0xcc00300
	v_mov_b32_e32 v169, 0x358637bd
	s_mov_b32 s91, 0x800000
	s_mov_b32 s92, 0xcc00000
	s_mov_b32 s93, 0x10800
	s_mov_b64 s[68:69], 0x8000
	s_mov_b32 s94, 0x8000
	v_mov_b32_e32 v170, 0x200
	v_xor_b32_e32 v159, 32, v164
	v_add_u32_e32 v165, 64, v0
	v_xor_b32_e32 v160, 16, v164
	v_xor_b32_e32 v161, 8, v164
	v_xor_b32_e32 v162, 4, v164
	v_xor_b32_e32 v163, 2, v164
	v_xor_b32_e32 v166, 1, v164
	v_mov_b32_e32 v124, 0x24060
	v_mov_b32_e32 v130, 0x24064
	v_mov_b32_e32 v132, 0x24068
	v_mov_b32_e32 v134, 0x2406c
	v_mov_b32_e32 v136, 0x24070
	v_mov_b32_e32 v138, 0x24074
	v_mov_b32_e32 v140, 0x24078
	v_mov_b32_e32 v142, 0x2407c
	v_mov_b32_e32 v171, 0xf149f2ca
	v_mov_b32_e32 v172, 0x7f800000
	s_barrier
	v_readfirstlane_b32 s100, v158
	s_lshr_b32 s100, s100, 6
	s_cmp_ge_u32 s100, 4
	s_cbranch_scc0 .Lap1_done
	s_setprio 1
.Lap1_done:
	s_branch .LBB0_177

; DI unsigned bar_ld(unsigned* p) { return __hip_atomic_load(p, __ATOMIC_RELAXED, __HIP_MEMORY_SCOPE_AGENT); }
; DI unsigned bar_add(unsigned* p, unsigned v) { return __hip_atomic_fetch_add(p, v, __ATOMIC_RELAXED, __HIP_MEMORY_SCOPE_AGENT); }
; DI void grid_barrier(unsigned* bar, unsigned k, volatile unsigned* meta) {
;   asm volatile("s_waitcnt vmcnt(0)" ::: "memory");
;   __syncthreads();
;   if (threadIdx.x == 0) {
;     const unsigned nloc = meta[0], nx = meta[1], x = meta[2];
;     const unsigned old = bar_add(bar + 1024 + 64 * x, 1u);
;     if (old + 1u == k * nloc) {
;       __builtin_amdgcn_fence(__ATOMIC_RELEASE, "agent");
;       asm volatile("s_waitcnt vmcnt(0)" ::: "memory");
;       const unsigned old2 = bar_add(bar + 3072, 1u);
;       if (old2 + 1u == k * nx) {
;         for (int j = 0; j < 16; ++j) __hip_atomic_store(bar + 2048 + 64 * j, k, __ATOMIC_RELAXED, __HIP_MEMORY_SCOPE_AGENT);
;       }
;     }
;     while (bar_ld(bar + 2048 + 64 * x) < k) __builtin_amdgcn_s_sleep(1);
;     __builtin_amdgcn_fence(__ATOMIC_ACQUIRE, "agent");
;     asm volatile("s_waitcnt vmcnt(0)" ::: "memory");
;   }
;   __syncthreads();
; }
.LBB0_265:
	s_setprio 0
	s_or_b64 exec, exec, s[6:7]
	s_waitcnt vmcnt(0)
	s_waitcnt lgkmcnt(0)
	s_barrier
	s_and_saveexec_b64 s[0:1], s[8:9]
	s_cbranch_execz .LBB0_275
	s_mov_b64 s[2:3], src_shared_base
	v_mov_b32_e32 v0, 0x24040
	ds_read_b32 v3, v0
	ds_read_b32 v2, v0 offset:4
	ds_read_b32 v0, v0 offset:8
	v_mov_b32_e32 v1, 0
	v_mov_b32_e32 v6, 1
	s_waitcnt lgkmcnt(0)
	v_mul_lo_u32 v3, v3, 6
	v_lshlrev_b32_e32 v0, 6, v0
	v_lshl_add_u64 v[0:1], v[0:1], 2, s[24:25]
	v_add_co_u32_e32 v4, vcc, 0xef01000, v0
	s_nop 1
	v_addc_co_u32_e32 v5, vcc, 0, v1, vcc
	global_atomic_add v4, v[4:5], v6, off offset:1024 sc0
	s_waitcnt vmcnt(0)
	v_add_u32_e32 v4, 1, v4
	v_cmp_eq_u32_e32 vcc, v4, v3
	s_and_saveexec_b64 s[2:3], vcc
	s_cbranch_execz .LBB0_271
	s_mov_b64 s[4:5], exec
	buffer_wbl2 sc1
	s_waitcnt vmcnt(0)
	v_mbcnt_lo_u32_b32 v3, s4, 0
	v_mbcnt_hi_u32_b32 v3, s5, v3
	v_cmp_eq_u32_e32 vcc, 0, v3
	s_and_saveexec_b64 s[6:7], vcc
	s_cbranch_execz .LBB0_269
	s_bcnt1_i32_b64 s4, s[4:5]
	v_mov_b32_e32 v4, 0xef03000
	v_mov_b32_e32 v5, s4
	global_atomic_add v4, v4, v5, s[24:25] offset:1024 sc0

; DI int ltid() { int t = threadIdx.x; asm volatile("" : "+v"(t)); return t; }
; template <int TYPE>
; DI void attn_item(const Params& p, int layer, int head, int qt, int dil, int res, int chunk, char* smem) {
;   const int tid = ltid(), lane = tid & 63, wid = tid >> 6, ql = lane & 31, h = lane >> 5;
;   const u16* proj = (const u16*)(p.ws + OFF_BIG);
;   constexpr int QC = TYPE == 0 ? 0 : TYPE == 1 ? 1152 : 1920;
;   constexpr int KC = TYPE == 0 ? 384 : TYPE == 1 ? 1408 : 2304;
;   constexpr int VC = TYPE == 0 ? 768 : TYPE == 1 ? 1664 : 2688;
;   const int qcol = QC + head * 64, kcol = KC + head * 64, vcol = VC + head * 64;
;   const int Q0 = qt * 256;
;   const int wq0 = Q0 + 32 * wid;
;   const int Uq = wq0 + ql;
;   const size_t tq = (size_t)Uq * dil + res;
;   bf16x8 qf[4];
; #pragma unroll
;   for (int ks = 0; ks < 4; ++ks) qf[ks] = *(const bf16x8*)(proj + tq * DIN + qcol + ks * 16 + h * 8);
;   char* sK = smem;
;   char* sV = smem + 8192;
;   volatile int* sflag = (volatile int*)(smem + FLG + 32);
;   volatile float* dred = (volatile float*)(smem + FLG + 96);
;   float slope = 0.f;
;   if (TYPE == 0) slope = exp2f(-8.f * (float)(head + 1) / 6.f) * (float)dil * LOG2E;
;   if (TYPE == 1) slope = exp2f(-2.f * (float)(head + 1)) * LOG2E;
;   const int wlim = (TYPE == 0) ? 128 : 0x3fffffff;
;   int kt_hi = (Q0 >> 6) + 3;
; DI void attn_phase(const Params& p, int layer, char* smem) {
;   int* counter = (int*)(p.ws + OFF_MISC) + layer * 4;
;   volatile int* s_item = (volatile int*)(smem + FLG);
;   for (;;) {
;     __syncthreads();
;     if (threadIdx.x == 0) *s_item = atomicAdd(counter, 1);
;     __syncthreads();
;     const int item = *s_item;
;     if (item >= 64 * (NCH3 + NCH2 + 2)) break;
;     int head, qt, ch;
;     if (item < 64 * NCH3) { head = 3; qt = 63 - item / NCH3; ch = (item % NCH3) | (NCH3 << 8); }
;     else if (item < 64 * (NCH3 + NCH2)) { const int j = item - 64 * NCH3; head = 2; qt = 63 - j / NCH2; ch = (j % NCH2) | (NCH2 << 8); }
;     else if (item < 64 * (NCH3 + NCH2 + 1)) { head = 1; qt = 63 - (item - 64 * (NCH3 + NCH2)); ch = 1 << 8; }
;     else { head = 0; qt = 63 - (item - 64 * (NCH3 + NCH2 + 1)); ch = 1 << 8; }
;     attn_item<1>(p, layer, head, qt, 1, 0, ch, smem);
;   }
;   for (;;) {
;     __syncthreads();
;     if (threadIdx.x == 0) *s_item = atomicAdd(counter + 1, 1);
.LBB0_549:
	s_or_b64 exec, exec, s[0:1]
	s_add_u32 s18, s24, 0xef00010
	s_addc_u32 s19, s25, 0
	s_mov_b64 s[6:7], src_shared_base
	s_add_u32 s36, s24, 0xef002b0
	s_mov_b32 s42, 0x41c00000
	s_mov_b32 s44, 2.0
	s_mov_b32 s46, 0x41000000
	s_mov_b32 s48, 0x41200000
	s_mov_b32 s52, 0x41800000
	s_mov_b32 s54, 0x41900000
	s_mov_b32 s56, 0x41d00000
	s_addc_u32 s37, s25, 0
	s_mov_b64 s[40:41], 0
	v_mov_b32_e32 v1, 0
	v_mov_b32_e32 v122, 0x24000
	v_mov_b32_e32 v125, s7
	v_mov_b32_e32 v126, 0x24000
	v_mov_b32_e32 v127, s7
	s_movk_i32 s6, 0x180
	s_movk_i32 s75, 0x80
	s_movk_i32 s76, 0x7f
	s_movk_i32 s77, 0xff
	s_movk_i32 s78, 0x13f
	s_movk_i32 s79, 0x1800
	s_mov_b32 s80, 0x3fb8aa3b
	s_mov_b32 s81, 0xf800000
	v_mov_b32_e32 v165, 0x260
	v_mov_b32_e32 v166, 0x3c23d70a
	s_mov_b32 s43, 0x41c80000
	s_mov_b32 s45, 0x40400000
	s_mov_b32 s47, 0x41100000
	s_mov_b32 s49, 0x41300000
	s_mov_b32 s53, 0x41880000
	s_mov_b32 s55, 0x41980000
	s_mov_b32 s57, 0x41d80000
	s_mov_b32 s82, 0xc2ce8ed0
	s_mov_b32 s83, 0x42b17218
	v_mov_b32_e32 v128, 0x3eb60549
	s_movk_i32 s84, 0x880
	s_mov_b64 s[58:59], 0xcc00300
	v_mov_b32_e32 v167, 0x358637bd
	s_mov_b32 s85, 0x800000
	s_mov_b32 s86, 0xcc00000
	s_mov_b32 s87, 0x10800
	s_mov_b64 s[60:61], 0x8000
	s_mov_b32 s88, 0x8000
	v_mov_b32_e32 v168, 0x200
	v_mov_b32_e32 v124, 0x24060
	v_mov_b32_e32 v130, 0x24064
	v_mov_b32_e32 v132, 0x24068
	v_mov_b32_e32 v134, 0x2406c
	v_mov_b32_e32 v136, 0x24070
	v_mov_b32_e32 v138, 0x24074
	v_mov_b32_e32 v140, 0x24078
	v_mov_b32_e32 v142, 0x2407c
	v_mov_b32_e32 v169, 0xf149f2ca
	v_mov_b32_e32 v170, 0x7f800000
	s_barrier
	v_readfirstlane_b32 s100, v158
	s_lshr_b32 s100, s100, 6
	s_cmp_ge_u32 s100, 4
	s_cbranch_scc0 .Lap2_done
	s_setprio 1

; DI unsigned bar_ld(unsigned* p) { return __hip_atomic_load(p, __ATOMIC_RELAXED, __HIP_MEMORY_SCOPE_AGENT); }
; DI unsigned bar_add(unsigned* p, unsigned v) { return __hip_atomic_fetch_add(p, v, __ATOMIC_RELAXED, __HIP_MEMORY_SCOPE_AGENT); }
; DI void grid_barrier(unsigned* bar, unsigned k, volatile unsigned* meta) {
;   asm volatile("s_waitcnt vmcnt(0)" ::: "memory");
;   __syncthreads();
;   if (threadIdx.x == 0) {
;     const unsigned nloc = meta[0], nx = meta[1], x = meta[2];
;     const unsigned old = bar_add(bar + 1024 + 64 * x, 1u);
;     if (old + 1u == k * nloc) {
;       __builtin_amdgcn_fence(__ATOMIC_RELEASE, "agent");
;       asm volatile("s_waitcnt vmcnt(0)" ::: "memory");
;       const unsigned old2 = bar_add(bar + 3072, 1u);
;       if (old2 + 1u == k * nx) {
;         for (int j = 0; j < 16; ++j) __hip_atomic_store(bar + 2048 + 64 * j, k, __ATOMIC_RELAXED, __HIP_MEMORY_SCOPE_AGENT);
;       }
;     }
;     while (bar_ld(bar + 2048 + 64 * x) < k) __builtin_amdgcn_s_sleep(1);
;     __builtin_amdgcn_fence(__ATOMIC_ACQUIRE, "agent");
;     asm volatile("s_waitcnt vmcnt(0)" ::: "memory");
;   }
;   __syncthreads();
; }
.LBB0_641:
	s_setprio 0
	s_or_b64 exec, exec, s[6:7]
	s_waitcnt vmcnt(0)
	s_waitcnt lgkmcnt(0)
	s_barrier
	s_and_saveexec_b64 s[0:1], s[8:9]
	s_cbranch_execz .LBB0_651
	s_mov_b64 s[2:3], src_shared_base
	v_mov_b32_e32 v0, 0x24040
	ds_read_b32 v3, v0
	ds_read_b32 v2, v0 offset:4
	ds_read_b32 v0, v0 offset:8
	v_mov_b32_e32 v1, 0
	v_mov_b32_e32 v6, 1
	s_waitcnt lgkmcnt(0)
	v_lshl_add_u32 v3, v3, 4, v3
	v_lshlrev_b32_e32 v0, 6, v0
	v_lshl_add_u64 v[0:1], v[0:1], 2, s[24:25]
	v_add_co_u32_e32 v4, vcc, 0xef01000, v0
	s_nop 1
	v_addc_co_u32_e32 v5, vcc, 0, v1, vcc
	global_atomic_add v4, v[4:5], v6, off offset:1024 sc0
	s_waitcnt vmcnt(0)
	v_add_u32_e32 v4, 1, v4
	v_cmp_eq_u32_e32 vcc, v4, v3
	s_and_saveexec_b64 s[2:3], vcc
	s_cbranch_execz .LBB0_647
	s_mov_b64 s[4:5], exec
	buffer_wbl2 sc1
	s_waitcnt vmcnt(0)
	v_mbcnt_lo_u32_b32 v3, s4, 0
	v_mbcnt_hi_u32_b32 v3, s5, v3
	v_cmp_eq_u32_e32 vcc, 0, v3
	s_and_saveexec_b64 s[6:7], vcc
	s_cbranch_execz .LBB0_645
	s_bcnt1_i32_b64 s4, s[4:5]
	v_mov_b32_e32 v4, 0xef03000
	v_mov_b32_e32 v5, s4
	global_atomic_add v4, v4, v5, s[24:25] offset:1024 sc0
